# matrix-core substitution: in-block steps take SrcB straight from the accumulator quad (4 wait states), second accumulator starts from inline zero
# speedup vs baseline: 1.0140x; 1.0012x over previous
; #define LAS __attribute__((address_space(3)))
; __device__ __forceinline__ float bf2f(unsigned short v) { return __uint_as_float(((unsigned)v) << 16); }
; __device__ __forceinline__ void dn_prep_item(const Args& a, LAS unsigned char* lds, int item, int tid, int wave, int lane, int& cwh, int next_item) {
;     ...
;         float x[64];
;         { const LAS unsigned char* src = lds + (tid < 128 ? L_V : L_KH) + 2 * (tid & 127); const LAS float* fac = tid < 128 ? betas : bks;
; #pragma unroll
;           for (int i = 0; i < 64; ++i) x[i] = bf2f(*(const LAS unsigned short*)(src + i * KS_)) * fac[i]; }
;         { const LAS float* lrow = Lm + (lane & 15);
.LBB0_878:
	s_and_b64 vcc, exec, s[22:23]
	s_cbranch_vccz .LBB0_880
	v_and_b32_e32 v234, 3, v206
	v_mul_u32_u24_e32 v234, 0x110, v234
	v_add_u32_e32 v234, 0x8800, v234
	ds_read_b128 v[88:91], v190
	ds_read_b128 v[92:95], v191
	ds_read_b128 v[96:99], v192
	ds_read_b128 v[100:103], v193
	ds_read_b128 v[104:107], v194
	ds_read_b128 v[108:111], v195
	ds_read_b128 v[112:115], v196
	ds_read_b128 v[116:119], v197
	ds_read_b128 v[120:123], v198
	ds_read_b128 v[124:127], v199
	ds_read_b128 v[128:131], v201
	ds_read_b128 v[132:135], v202
	ds_read_b128 v[136:139], v203
	ds_read_b128 v[140:143], v204
	ds_read_b128 v[144:147], v205
	ds_read_b128 v[236:239], v207
	ds_read_u16 v0, v189
	ds_read_u16 v1, v189 offset:272
	ds_read_u16 v2, v189 offset:544
	ds_read_u16 v3, v189 offset:816
	ds_read_u16 v4, v189 offset:1088
	ds_read_u16 v5, v189 offset:1360
	ds_read_u16 v6, v189 offset:1632
	ds_read_u16 v7, v189 offset:1904
	ds_read_u16 v8, v189 offset:2176
	ds_read_u16 v9, v189 offset:2448
	ds_read_u16 v10, v189 offset:2720
	ds_read_u16 v11, v189 offset:2992
	ds_read_u16 v12, v189 offset:3264
	ds_read_u16 v13, v189 offset:3536
	ds_read_u16 v14, v189 offset:3808
	ds_read_u16 v15, v189 offset:4080
	ds_read_u16 v16, v189 offset:4352
	ds_read_u16 v17, v189 offset:4624
	ds_read_u16 v18, v189 offset:4896
	ds_read_u16 v19, v189 offset:5168
	ds_read_u16 v20, v189 offset:5440
	ds_read_u16 v21, v189 offset:5712
	ds_read_u16 v22, v189 offset:5984
	ds_read_u16 v23, v189 offset:6256
	ds_read_u16 v24, v189 offset:6528
	ds_read_u16 v25, v189 offset:6800
	ds_read_u16 v26, v189 offset:7072
	ds_read_u16 v27, v189 offset:7344
	ds_read_u16 v28, v189 offset:7616
	ds_read_u16 v29, v189 offset:7888
	ds_read_u16 v30, v189 offset:8160
	ds_read_u16 v31, v189 offset:8432
	ds_read_u16 v32, v189 offset:8704
	ds_read_u16 v33, v189 offset:8976
	ds_read_u16 v34, v189 offset:9248
	ds_read_u16 v35, v189 offset:9520
	ds_read_u16 v36, v189 offset:9792
	ds_read_u16 v37, v189 offset:10064
	ds_read_u16 v38, v189 offset:10336
	ds_read_u16 v39, v189 offset:10608
	ds_read_u16 v40, v189 offset:10880
	ds_read_u16 v41, v189 offset:11152
	ds_read_u16 v42, v189 offset:11424
	ds_read_u16 v43, v189 offset:11696
	ds_read_u16 v44, v189 offset:11968
	ds_read_u16 v45, v189 offset:12240
	ds_read_u16 v46, v189 offset:12512
	ds_read_u16 v47, v189 offset:12784
	ds_read_u16 v72, v189 offset:13056
	ds_read_u16 v73, v189 offset:13328
	ds_read_u16 v74, v189 offset:13600
	ds_read_u16 v75, v189 offset:13872
	ds_read_u16 v76, v189 offset:14144
	ds_read_u16 v77, v189 offset:14416
	ds_read_u16 v78, v189 offset:14688
	ds_read_u16 v79, v189 offset:14960
	ds_read_u16 v80, v189 offset:15232
	ds_read_u16 v81, v189 offset:15504
	ds_read_u16 v82, v189 offset:15776
	ds_read_u16 v83, v189 offset:16048
	ds_read_u16 v84, v189 offset:16320
	ds_read_u16 v85, v189 offset:16592
	ds_read_u16 v86, v189 offset:16864
	ds_read_u16 v87, v189 offset:17136
	s_waitcnt lgkmcnt(0)
	v_lshlrev_b32_e32 v0, 16, v0
	v_lshlrev_b32_e32 v1, 16, v1
	v_lshlrev_b32_e32 v2, 16, v2
	v_lshlrev_b32_e32 v3, 16, v3
	v_lshlrev_b32_e32 v4, 16, v4
	v_lshlrev_b32_e32 v5, 16, v5
	v_lshlrev_b32_e32 v6, 16, v6
	v_lshlrev_b32_e32 v7, 16, v7
	v_lshlrev_b32_e32 v8, 16, v8
	v_lshlrev_b32_e32 v9, 16, v9
	v_lshlrev_b32_e32 v10, 16, v10
	v_lshlrev_b32_e32 v11, 16, v11
	v_lshlrev_b32_e32 v12, 16, v12
	v_lshlrev_b32_e32 v13, 16, v13
	v_lshlrev_b32_e32 v14, 16, v14
	v_lshlrev_b32_e32 v15, 16, v15
	v_lshlrev_b32_e32 v16, 16, v16
	v_lshlrev_b32_e32 v17, 16, v17
	v_lshlrev_b32_e32 v18, 16, v18
	v_lshlrev_b32_e32 v19, 16, v19
	v_lshlrev_b32_e32 v20, 16, v20
	v_lshlrev_b32_e32 v21, 16, v21
	v_lshlrev_b32_e32 v22, 16, v22
	v_lshlrev_b32_e32 v23, 16, v23
	v_lshlrev_b32_e32 v24, 16, v24
	v_lshlrev_b32_e32 v25, 16, v25
	v_lshlrev_b32_e32 v26, 16, v26
	v_lshlrev_b32_e32 v27, 16, v27
	v_lshlrev_b32_e32 v28, 16, v28
	v_lshlrev_b32_e32 v29, 16, v29
	v_lshlrev_b32_e32 v30, 16, v30
	v_lshlrev_b32_e32 v31, 16, v31
	v_lshlrev_b32_e32 v32, 16, v32
	v_lshlrev_b32_e32 v33, 16, v33
	v_lshlrev_b32_e32 v34, 16, v34
	v_lshlrev_b32_e32 v35, 16, v35
	v_lshlrev_b32_e32 v36, 16, v36
	v_lshlrev_b32_e32 v37, 16, v37
	v_lshlrev_b32_e32 v38, 16, v38
	v_lshlrev_b32_e32 v39, 16, v39
	v_lshlrev_b32_e32 v40, 16, v40
	v_lshlrev_b32_e32 v41, 16, v41
	v_lshlrev_b32_e32 v42, 16, v42
	v_lshlrev_b32_e32 v43, 16, v43
	v_lshlrev_b32_e32 v44, 16, v44
	v_lshlrev_b32_e32 v45, 16, v45
	v_lshlrev_b32_e32 v46, 16, v46
	v_lshlrev_b32_e32 v47, 16, v47
	v_lshlrev_b32_e32 v72, 16, v72
	v_lshlrev_b32_e32 v73, 16, v73
	v_lshlrev_b32_e32 v74, 16, v74
	v_lshlrev_b32_e32 v75, 16, v75
	v_lshlrev_b32_e32 v76, 16, v76
	v_lshlrev_b32_e32 v77, 16, v77
	v_lshlrev_b32_e32 v78, 16, v78
	v_lshlrev_b32_e32 v79, 16, v79
	v_lshlrev_b32_e32 v80, 16, v80
	v_lshlrev_b32_e32 v81, 16, v81
	v_lshlrev_b32_e32 v82, 16, v82
	v_lshlrev_b32_e32 v83, 16, v83
	v_lshlrev_b32_e32 v84, 16, v84
	v_lshlrev_b32_e32 v85, 16, v85
	v_lshlrev_b32_e32 v86, 16, v86
	v_lshlrev_b32_e32 v87, 16, v87
	v_mul_f32_e32 v0, v88, v0
	v_mul_f32_e32 v1, v89, v1
	v_mul_f32_e32 v2, v90, v2
	v_mul_f32_e32 v3, v91, v3
	v_mul_f32_e32 v4, v92, v4
	v_mul_f32_e32 v5, v93, v5
	v_mul_f32_e32 v6, v94, v6
	v_mul_f32_e32 v7, v95, v7
	v_mul_f32_e32 v8, v96, v8
	v_mul_f32_e32 v9, v97, v9
	v_mul_f32_e32 v10, v98, v10
	v_mul_f32_e32 v11, v99, v11
	v_mul_f32_e32 v12, v100, v12
	v_mul_f32_e32 v13, v101, v13
	v_mul_f32_e32 v14, v102, v14
	v_mul_f32_e32 v15, v103, v15
	v_mul_f32_e32 v16, v104, v16
	v_mul_f32_e32 v17, v105, v17
	v_mul_f32_e32 v18, v106, v18
	v_mul_f32_e32 v19, v107, v19
	v_mul_f32_e32 v20, v108, v20
	v_mul_f32_e32 v21, v109, v21
	v_mul_f32_e32 v22, v110, v22
	v_mul_f32_e32 v23, v111, v23
; #define LAS __attribute__((address_space(3)))
; __device__ __forceinline__ float bf2f(unsigned short v) { return __uint_as_float(((unsigned)v) << 16); }
; __device__ __forceinline__ void dn_prep_item(const Args& a, LAS unsigned char* lds, int item, int tid, int wave, int lane, int& cwh, int next_item) {
;     ...
;         { const LAS unsigned char* src = lds + (tid < 128 ? L_V : L_KH) + 2 * (tid & 127); const LAS float* fac = tid < 128 ? betas : bks;
; #pragma unroll
;           for (int i = 0; i < 64; ++i) x[i] = bf2f(*(const LAS unsigned short*)(src + i * KS_)) * fac[i]; }
;         { const LAS float* lrow = Lm + (lane & 15);
; #pragma unroll
;         for (int i = 1; i < 64; ++i) { float sa[4] = { x[i], 0.f, 0.f, 0.f };
;             int lr[4];
; #pragma unroll
;             for (int g = 0; g < (i + 15) / 16; ++g) lr[g] = __float_as_int(lrow[i * 68 + 16 * g]);
; #pragma unroll
;             for (int j = 0; j < i; ++j) { fmac_rowbcast_sel(sa[j & 3], lr[j >> 4], x[j], j); }
;             x[i] = (sa[0] + sa[1]) + (sa[2] + sa[3]); } }
	v_mul_f32_e32 v24, v112, v24
	v_mul_f32_e32 v25, v113, v25
	v_mul_f32_e32 v26, v114, v26
	v_mul_f32_e32 v27, v115, v27
	v_mul_f32_e32 v28, v116, v28
	v_mul_f32_e32 v29, v117, v29
	v_mul_f32_e32 v30, v118, v30
	v_mul_f32_e32 v31, v119, v31
	v_mul_f32_e32 v32, v120, v32
	v_mul_f32_e32 v33, v121, v33
	v_mul_f32_e32 v34, v122, v34
	v_mul_f32_e32 v35, v123, v35
	v_mul_f32_e32 v36, v124, v36
	v_mul_f32_e32 v37, v125, v37
	v_mul_f32_e32 v38, v126, v38
	v_mul_f32_e32 v39, v127, v39
	v_mul_f32_e32 v40, v128, v40
	v_mul_f32_e32 v41, v129, v41
	v_mul_f32_e32 v42, v130, v42
	v_mul_f32_e32 v43, v131, v43
	v_mul_f32_e32 v44, v132, v44
	v_mul_f32_e32 v45, v133, v45
	v_mul_f32_e32 v46, v134, v46
	v_mul_f32_e32 v47, v135, v47
	v_mul_f32_e32 v72, v136, v72
	v_mul_f32_e32 v73, v137, v73
	v_mul_f32_e32 v74, v138, v74
	v_mul_f32_e32 v75, v139, v75
	v_mul_f32_e32 v76, v140, v76
	v_mul_f32_e32 v77, v141, v77
	v_mul_f32_e32 v78, v142, v78
	v_mul_f32_e32 v79, v143, v79
	v_mul_f32_e32 v80, v144, v80
	v_mul_f32_e32 v81, v145, v81
	v_mul_f32_e32 v82, v146, v82
	v_mul_f32_e32 v83, v147, v83
	v_mul_f32_e32 v84, v236, v84
	v_mul_f32_e32 v85, v237, v85
	v_mul_f32_e32 v86, v238, v86
	v_mul_f32_e32 v87, v239, v87
	ds_read_b128 v[88:91], v234 offset:0
	ds_read_b128 v[104:107], v234 offset:1088
	ds_read_b128 v[108:111], v234 offset:1104
	ds_read_b128 v[120:123], v234 offset:2176
	ds_read_b128 v[124:127], v234 offset:2192
	ds_read_b128 v[128:131], v234 offset:2208
	s_waitcnt lgkmcnt(5)
	s_nop 4
	s_nop 3
	v_mfma_f32_4x4x1_16b_f32 v[0:3], v88, v0, v[0:3]
	s_nop 3
	v_mfma_f32_4x4x1_16b_f32 v[0:3], v89, v1, v[0:3]
	s_nop 3
	v_mfma_f32_4x4x1_16b_f32 v[0:3], v90, v2, v[0:3]
	ds_read_b128 v[88:91], v234 offset:3264
	ds_read_b128 v[92:95], v234 offset:3280
	ds_read_b128 v[96:99], v234 offset:3296
	ds_read_b128 v[100:103], v234 offset:3312
	s_waitcnt lgkmcnt(7)
	s_nop 4
	v_mfma_f32_4x4x1_16b_f32 v[4:7], v104, v0, v[4:7]
	v_mfma_f32_4x4x1_16b_f32 v[240:243], v105, v1, 0
	s_nop 0
	v_mfma_f32_4x4x1_16b_f32 v[4:7], v106, v2, v[4:7]
	v_mfma_f32_4x4x1_16b_f32 v[240:243], v107, v3, v[240:243]
	s_nop 0
	s_nop 3
	v_pk_add_f32 v[4:5], v[4:5], v[240:241]
	v_pk_add_f32 v[6:7], v[6:7], v[242:243]
	s_nop 3
	v_mfma_f32_4x4x1_16b_f32 v[4:7], v108, v4, v[4:7]
	s_nop 3
	v_mfma_f32_4x4x1_16b_f32 v[4:7], v109, v5, v[4:7]
	s_nop 3
	v_mfma_f32_4x4x1_16b_f32 v[4:7], v110, v6, v[4:7]
	ds_read_b128 v[104:107], v234 offset:4352
	ds_read_b128 v[108:111], v234 offset:4368
	ds_read_b128 v[112:115], v234 offset:4384
	ds_read_b128 v[116:119], v234 offset:4400
	s_waitcnt lgkmcnt(8)
	s_nop 4
	v_mfma_f32_4x4x1_16b_f32 v[8:11], v120, v0, v[8:11]
	v_mfma_f32_4x4x1_16b_f32 v[240:243], v121, v1, 0
	s_nop 0
	v_mfma_f32_4x4x1_16b_f32 v[8:11], v122, v2, v[8:11]
	v_mfma_f32_4x4x1_16b_f32 v[240:243], v123, v3, v[240:243]
	s_nop 0
	v_mfma_f32_4x4x1_16b_f32 v[8:11], v124, v4, v[8:11]
	v_mfma_f32_4x4x1_16b_f32 v[240:243], v125, v5, v[240:243]
	s_nop 0
	v_mfma_f32_4x4x1_16b_f32 v[8:11], v126, v6, v[8:11]
	v_mfma_f32_4x4x1_16b_f32 v[240:243], v127, v7, v[240:243]
	s_nop 0
	s_nop 3
	v_pk_add_f32 v[8:9], v[8:9], v[240:241]
	v_pk_add_f32 v[10:11], v[10:11], v[242:243]
	s_nop 3
	v_mfma_f32_4x4x1_16b_f32 v[8:11], v128, v8, v[8:11]
	s_nop 3
	v_mfma_f32_4x4x1_16b_f32 v[8:11], v129, v9, v[8:11]
	s_nop 3
	v_mfma_f32_4x4x1_16b_f32 v[8:11], v130, v10, v[8:11]
	ds_read_b128 v[120:123], v234 offset:4416
	s_waitcnt lgkmcnt(5)
	s_nop 4
	v_mfma_f32_4x4x1_16b_f32 v[12:15], v88, v0, v[12:15]
	v_mfma_f32_4x4x1_16b_f32 v[240:243], v89, v1, 0
	s_nop 0
	v_mfma_f32_4x4x1_16b_f32 v[12:15], v90, v2, v[12:15]
	v_mfma_f32_4x4x1_16b_f32 v[240:243], v91, v3, v[240:243]
	s_nop 0
	v_mfma_f32_4x4x1_16b_f32 v[12:15], v92, v4, v[12:15]
	v_mfma_f32_4x4x1_16b_f32 v[240:243], v93, v5, v[240:243]
	s_nop 0
	v_mfma_f32_4x4x1_16b_f32 v[12:15], v94, v6, v[12:15]
	v_mfma_f32_4x4x1_16b_f32 v[240:243], v95, v7, v[240:243]
	s_nop 0
	v_mfma_f32_4x4x1_16b_f32 v[12:15], v96, v8, v[12:15]
	v_mfma_f32_4x4x1_16b_f32 v[240:243], v97, v9, v[240:243]
	s_nop 0
	v_mfma_f32_4x4x1_16b_f32 v[12:15], v98, v10, v[12:15]
	v_mfma_f32_4x4x1_16b_f32 v[240:243], v99, v11, v[240:243]
	s_nop 0
	s_nop 3
	v_pk_add_f32 v[12:13], v[12:13], v[240:241]
	v_pk_add_f32 v[14:15], v[14:15], v[242:243]
	s_nop 3
	v_mfma_f32_4x4x1_16b_f32 v[12:15], v100, v12, v[12:15]
	s_nop 3
	v_mfma_f32_4x4x1_16b_f32 v[12:15], v101, v13, v[12:15]
	s_nop 3
	v_mfma_f32_4x4x1_16b_f32 v[12:15], v102, v14, v[12:15]
	ds_read_b128 v[88:91], v234 offset:5440
	ds_read_b128 v[92:95], v234 offset:5456
	ds_read_b128 v[96:99], v234 offset:5472
	ds_read_b128 v[100:103], v234 offset:5488
	s_waitcnt lgkmcnt(5)
	s_nop 4
	v_mfma_f32_4x4x1_16b_f32 v[16:19], v104, v0, v[16:19]
	v_mfma_f32_4x4x1_16b_f32 v[240:243], v105, v1, 0
	s_nop 0
	v_mfma_f32_4x4x1_16b_f32 v[16:19], v106, v2, v[16:19]
	v_mfma_f32_4x4x1_16b_f32 v[240:243], v107, v3, v[240:243]
	s_nop 0
	v_mfma_f32_4x4x1_16b_f32 v[16:19], v108, v4, v[16:19]
	v_mfma_f32_4x4x1_16b_f32 v[240:243], v109, v5, v[240:243]
	s_nop 0
	v_mfma_f32_4x4x1_16b_f32 v[16:19], v110, v6, v[16:19]
	v_mfma_f32_4x4x1_16b_f32 v[240:243], v111, v7, v[240:243]
	s_nop 0
	v_mfma_f32_4x4x1_16b_f32 v[16:19], v112, v8, v[16:19]
	v_mfma_f32_4x4x1_16b_f32 v[240:243], v113, v9, v[240:243]
	s_nop 0
	v_mfma_f32_4x4x1_16b_f32 v[16:19], v114, v10, v[16:19]
	v_mfma_f32_4x4x1_16b_f32 v[240:243], v115, v11, v[240:243]
	s_nop 0
	v_mfma_f32_4x4x1_16b_f32 v[16:19], v116, v12, v[16:19]
	v_mfma_f32_4x4x1_16b_f32 v[240:243], v117, v13, v[240:243]
	s_nop 0
	v_mfma_f32_4x4x1_16b_f32 v[16:19], v118, v14, v[16:19]
	v_mfma_f32_4x4x1_16b_f32 v[240:243], v119, v15, v[240:243]
	s_nop 0
	s_nop 3
	v_pk_add_f32 v[16:17], v[16:17], v[240:241]
	v_pk_add_f32 v[18:19], v[18:19], v[242:243]
	ds_read_b128 v[104:107], v234 offset:5504
	ds_read_b128 v[108:111], v234 offset:5520
	s_waitcnt lgkmcnt(6)
; #define LAS __attribute__((address_space(3)))
; __device__ __forceinline__ void dn_prep_item(const Args& a, LAS unsigned char* lds, int item, int tid, int wave, int lane, int& cwh, int next_item) {
;     ...
;         { const LAS float* lrow = Lm + (lane & 15);
; #pragma unroll
;         for (int i = 1; i < 64; ++i) { float sa[4] = { x[i], 0.f, 0.f, 0.f };
;             int lr[4];
; #pragma unroll
;             for (int g = 0; g < (i + 15) / 16; ++g) lr[g] = __float_as_int(lrow[i * 68 + 16 * g]);
; #pragma unroll
;             for (int j = 0; j < i; ++j) { fmac_rowbcast_sel(sa[j & 3], lr[j >> 4], x[j], j); }
;             x[i] = (sa[0] + sa[1]) + (sa[2] + sa[3]); } }
	s_nop 3
	v_mfma_f32_4x4x1_16b_f32 v[16:19], v120, v16, v[16:19]
	s_nop 3
	v_mfma_f32_4x4x1_16b_f32 v[16:19], v121, v17, v[16:19]
	s_nop 3
	v_mfma_f32_4x4x1_16b_f32 v[16:19], v122, v18, v[16:19]
	ds_read_b128 v[120:123], v234 offset:6528
	ds_read_b128 v[124:127], v234 offset:6544
	ds_read_b128 v[128:131], v234 offset:6560
	ds_read_b128 v[132:135], v234 offset:6576
	s_waitcnt lgkmcnt(6)
	s_nop 4
	v_mfma_f32_4x4x1_16b_f32 v[20:23], v88, v0, v[20:23]
	v_mfma_f32_4x4x1_16b_f32 v[240:243], v89, v1, 0
	s_nop 0
	v_mfma_f32_4x4x1_16b_f32 v[20:23], v90, v2, v[20:23]
	v_mfma_f32_4x4x1_16b_f32 v[240:243], v91, v3, v[240:243]
	s_nop 0
	v_mfma_f32_4x4x1_16b_f32 v[20:23], v92, v4, v[20:23]
	v_mfma_f32_4x4x1_16b_f32 v[240:243], v93, v5, v[240:243]
	s_nop 0
	v_mfma_f32_4x4x1_16b_f32 v[20:23], v94, v6, v[20:23]
	v_mfma_f32_4x4x1_16b_f32 v[240:243], v95, v7, v[240:243]
	s_nop 0
	v_mfma_f32_4x4x1_16b_f32 v[20:23], v96, v8, v[20:23]
	v_mfma_f32_4x4x1_16b_f32 v[240:243], v97, v9, v[240:243]
	s_nop 0
	v_mfma_f32_4x4x1_16b_f32 v[20:23], v98, v10, v[20:23]
	v_mfma_f32_4x4x1_16b_f32 v[240:243], v99, v11, v[240:243]
	s_nop 0
	v_mfma_f32_4x4x1_16b_f32 v[20:23], v100, v12, v[20:23]
	v_mfma_f32_4x4x1_16b_f32 v[240:243], v101, v13, v[240:243]
	s_nop 0
	v_mfma_f32_4x4x1_16b_f32 v[20:23], v102, v14, v[20:23]
	v_mfma_f32_4x4x1_16b_f32 v[240:243], v103, v15, v[240:243]
	s_nop 0
	ds_read_b128 v[88:91], v234 offset:6592
	ds_read_b128 v[92:95], v234 offset:6608
	ds_read_b128 v[96:99], v234 offset:6624
	s_waitcnt lgkmcnt(7)
	v_mfma_f32_4x4x1_16b_f32 v[20:23], v104, v16, v[20:23]
	v_mfma_f32_4x4x1_16b_f32 v[240:243], v105, v17, v[240:243]
	s_nop 0
	v_mfma_f32_4x4x1_16b_f32 v[20:23], v106, v18, v[20:23]
	v_mfma_f32_4x4x1_16b_f32 v[240:243], v107, v19, v[240:243]
	s_nop 0
	s_nop 3
	v_pk_add_f32 v[20:21], v[20:21], v[240:241]
	v_pk_add_f32 v[22:23], v[22:23], v[242:243]
	s_nop 3
	v_mfma_f32_4x4x1_16b_f32 v[20:23], v108, v20, v[20:23]
	s_nop 3
	v_mfma_f32_4x4x1_16b_f32 v[20:23], v109, v21, v[20:23]
	s_nop 3
	v_mfma_f32_4x4x1_16b_f32 v[20:23], v110, v22, v[20:23]
	ds_read_b128 v[104:107], v234 offset:7616
	ds_read_b128 v[108:111], v234 offset:7632
	ds_read_b128 v[112:115], v234 offset:7648
	ds_read_b128 v[116:119], v234 offset:7664
	s_waitcnt lgkmcnt(7)
	s_nop 4
	v_mfma_f32_4x4x1_16b_f32 v[24:27], v120, v0, v[24:27]
	v_mfma_f32_4x4x1_16b_f32 v[240:243], v121, v1, 0
	s_nop 0
	v_mfma_f32_4x4x1_16b_f32 v[24:27], v122, v2, v[24:27]
	v_mfma_f32_4x4x1_16b_f32 v[240:243], v123, v3, v[240:243]
	s_nop 0
	v_mfma_f32_4x4x1_16b_f32 v[24:27], v124, v4, v[24:27]
	v_mfma_f32_4x4x1_16b_f32 v[240:243], v125, v5, v[240:243]
	s_nop 0
	v_mfma_f32_4x4x1_16b_f32 v[24:27], v126, v6, v[24:27]
	v_mfma_f32_4x4x1_16b_f32 v[240:243], v127, v7, v[240:243]
	s_nop 0
	v_mfma_f32_4x4x1_16b_f32 v[24:27], v128, v8, v[24:27]
	v_mfma_f32_4x4x1_16b_f32 v[240:243], v129, v9, v[240:243]
	s_nop 0
	v_mfma_f32_4x4x1_16b_f32 v[24:27], v130, v10, v[24:27]
	v_mfma_f32_4x4x1_16b_f32 v[240:243], v131, v11, v[240:243]
	s_nop 0
	v_mfma_f32_4x4x1_16b_f32 v[24:27], v132, v12, v[24:27]
	v_mfma_f32_4x4x1_16b_f32 v[240:243], v133, v13, v[240:243]
	s_nop 0
	v_mfma_f32_4x4x1_16b_f32 v[24:27], v134, v14, v[24:27]
	v_mfma_f32_4x4x1_16b_f32 v[240:243], v135, v15, v[240:243]
	s_nop 0
	ds_read_b128 v[120:123], v234 offset:7680
	ds_read_b128 v[124:127], v234 offset:7696
	ds_read_b128 v[128:131], v234 offset:7712
	ds_read_b128 v[132:135], v234 offset:7728
	s_waitcnt lgkmcnt(8)
	v_mfma_f32_4x4x1_16b_f32 v[24:27], v88, v16, v[24:27]
	v_mfma_f32_4x4x1_16b_f32 v[240:243], v89, v17, v[240:243]
	s_nop 0
	v_mfma_f32_4x4x1_16b_f32 v[24:27], v90, v18, v[24:27]
	v_mfma_f32_4x4x1_16b_f32 v[240:243], v91, v19, v[240:243]
	s_nop 0
	v_mfma_f32_4x4x1_16b_f32 v[24:27], v92, v20, v[24:27]
	v_mfma_f32_4x4x1_16b_f32 v[240:243], v93, v21, v[240:243]
	s_nop 0
	v_mfma_f32_4x4x1_16b_f32 v[24:27], v94, v22, v[24:27]
	v_mfma_f32_4x4x1_16b_f32 v[240:243], v95, v23, v[240:243]
	s_nop 0
	s_nop 3
	v_pk_add_f32 v[24:25], v[24:25], v[240:241]
	v_pk_add_f32 v[26:27], v[26:27], v[242:243]
	s_nop 3
	v_mfma_f32_4x4x1_16b_f32 v[24:27], v96, v24, v[24:27]
	s_nop 3
	v_mfma_f32_4x4x1_16b_f32 v[24:27], v97, v25, v[24:27]
	s_nop 3
	v_mfma_f32_4x4x1_16b_f32 v[24:27], v98, v26, v[24:27]
	ds_read_b128 v[88:91], v234 offset:8704
	ds_read_b128 v[92:95], v234 offset:8720
	ds_read_b128 v[96:99], v234 offset:8736
	ds_read_b128 v[100:103], v234 offset:8752
	s_waitcnt lgkmcnt(8)
	s_nop 4
	v_mfma_f32_4x4x1_16b_f32 v[28:31], v104, v0, v[28:31]
	v_mfma_f32_4x4x1_16b_f32 v[240:243], v105, v1, 0
	s_nop 0
	v_mfma_f32_4x4x1_16b_f32 v[28:31], v106, v2, v[28:31]
	v_mfma_f32_4x4x1_16b_f32 v[240:243], v107, v3, v[240:243]
	s_nop 0
	v_mfma_f32_4x4x1_16b_f32 v[28:31], v108, v4, v[28:31]
	v_mfma_f32_4x4x1_16b_f32 v[240:243], v109, v5, v[240:243]
	s_nop 0
	v_mfma_f32_4x4x1_16b_f32 v[28:31], v110, v6, v[28:31]
	v_mfma_f32_4x4x1_16b_f32 v[240:243], v111, v7, v[240:243]
	s_nop 0
	v_mfma_f32_4x4x1_16b_f32 v[28:31], v112, v8, v[28:31]
	v_mfma_f32_4x4x1_16b_f32 v[240:243], v113, v9, v[240:243]
	s_nop 0
	v_mfma_f32_4x4x1_16b_f32 v[28:31], v114, v10, v[28:31]
	v_mfma_f32_4x4x1_16b_f32 v[240:243], v115, v11, v[240:243]
	s_nop 0
	v_mfma_f32_4x4x1_16b_f32 v[28:31], v116, v12, v[28:31]
	v_mfma_f32_4x4x1_16b_f32 v[240:243], v117, v13, v[240:243]
	s_nop 0
	v_mfma_f32_4x4x1_16b_f32 v[28:31], v118, v14, v[28:31]
	v_mfma_f32_4x4x1_16b_f32 v[240:243], v119, v15, v[240:243]
	s_nop 0
	ds_read_b128 v[104:107], v234 offset:8768
	ds_read_b128 v[108:111], v234 offset:8784
	ds_read_b128 v[112:115], v234 offset:8800
	ds_read_b128 v[116:119], v234 offset:8816
	s_waitcnt lgkmcnt(8)
; #define LAS __attribute__((address_space(3)))
; __device__ __forceinline__ void dn_prep_item(const Args& a, LAS unsigned char* lds, int item, int tid, int wave, int lane, int& cwh, int next_item) {
;     ...
;         { const LAS float* lrow = Lm + (lane & 15);
; #pragma unroll
;         for (int i = 1; i < 64; ++i) { float sa[4] = { x[i], 0.f, 0.f, 0.f };
;             int lr[4];
; #pragma unroll
;             for (int g = 0; g < (i + 15) / 16; ++g) lr[g] = __float_as_int(lrow[i * 68 + 16 * g]);
; #pragma unroll
;             for (int j = 0; j < i; ++j) { fmac_rowbcast_sel(sa[j & 3], lr[j >> 4], x[j], j); }
;             x[i] = (sa[0] + sa[1]) + (sa[2] + sa[3]); } }
	v_mfma_f32_4x4x1_16b_f32 v[28:31], v120, v16, v[28:31]
	v_mfma_f32_4x4x1_16b_f32 v[240:243], v121, v17, v[240:243]
	s_nop 0
	v_mfma_f32_4x4x1_16b_f32 v[28:31], v122, v18, v[28:31]
	v_mfma_f32_4x4x1_16b_f32 v[240:243], v123, v19, v[240:243]
	s_nop 0
	v_mfma_f32_4x4x1_16b_f32 v[28:31], v124, v20, v[28:31]
	v_mfma_f32_4x4x1_16b_f32 v[240:243], v125, v21, v[240:243]
	s_nop 0
	v_mfma_f32_4x4x1_16b_f32 v[28:31], v126, v22, v[28:31]
	v_mfma_f32_4x4x1_16b_f32 v[240:243], v127, v23, v[240:243]
	s_nop 0
	v_mfma_f32_4x4x1_16b_f32 v[28:31], v128, v24, v[28:31]
	v_mfma_f32_4x4x1_16b_f32 v[240:243], v129, v25, v[240:243]
	s_nop 0
	v_mfma_f32_4x4x1_16b_f32 v[28:31], v130, v26, v[28:31]
	v_mfma_f32_4x4x1_16b_f32 v[240:243], v131, v27, v[240:243]
	s_nop 0
	s_nop 3
	v_pk_add_f32 v[28:29], v[28:29], v[240:241]
	v_pk_add_f32 v[30:31], v[30:31], v[242:243]
	s_nop 3
	v_mfma_f32_4x4x1_16b_f32 v[28:31], v132, v28, v[28:31]
	s_nop 3
	v_mfma_f32_4x4x1_16b_f32 v[28:31], v133, v29, v[28:31]
	s_nop 3
	v_mfma_f32_4x4x1_16b_f32 v[28:31], v134, v30, v[28:31]
	ds_read_b128 v[120:123], v234 offset:8832
	s_waitcnt lgkmcnt(5)
	s_nop 4
	v_mfma_f32_4x4x1_16b_f32 v[32:35], v88, v0, v[32:35]
	v_mfma_f32_4x4x1_16b_f32 v[240:243], v89, v1, 0
	s_nop 0
	v_mfma_f32_4x4x1_16b_f32 v[32:35], v90, v2, v[32:35]
	v_mfma_f32_4x4x1_16b_f32 v[240:243], v91, v3, v[240:243]
	s_nop 0
	v_mfma_f32_4x4x1_16b_f32 v[32:35], v92, v4, v[32:35]
	v_mfma_f32_4x4x1_16b_f32 v[240:243], v93, v5, v[240:243]
	s_nop 0
	v_mfma_f32_4x4x1_16b_f32 v[32:35], v94, v6, v[32:35]
	v_mfma_f32_4x4x1_16b_f32 v[240:243], v95, v7, v[240:243]
	s_nop 0
	v_mfma_f32_4x4x1_16b_f32 v[32:35], v96, v8, v[32:35]
	v_mfma_f32_4x4x1_16b_f32 v[240:243], v97, v9, v[240:243]
	s_nop 0
	v_mfma_f32_4x4x1_16b_f32 v[32:35], v98, v10, v[32:35]
	v_mfma_f32_4x4x1_16b_f32 v[240:243], v99, v11, v[240:243]
	s_nop 0
	v_mfma_f32_4x4x1_16b_f32 v[32:35], v100, v12, v[32:35]
	v_mfma_f32_4x4x1_16b_f32 v[240:243], v101, v13, v[240:243]
	s_nop 0
	v_mfma_f32_4x4x1_16b_f32 v[32:35], v102, v14, v[32:35]
	v_mfma_f32_4x4x1_16b_f32 v[240:243], v103, v15, v[240:243]
	s_nop 0
	ds_read_b128 v[88:91], v234 offset:9792
	ds_read_b128 v[92:95], v234 offset:9808
	ds_read_b128 v[96:99], v234 offset:9824
	ds_read_b128 v[100:103], v234 offset:9840
	s_waitcnt lgkmcnt(5)
	v_mfma_f32_4x4x1_16b_f32 v[32:35], v104, v16, v[32:35]
	v_mfma_f32_4x4x1_16b_f32 v[240:243], v105, v17, v[240:243]
	s_nop 0
	v_mfma_f32_4x4x1_16b_f32 v[32:35], v106, v18, v[32:35]
	v_mfma_f32_4x4x1_16b_f32 v[240:243], v107, v19, v[240:243]
	s_nop 0
	v_mfma_f32_4x4x1_16b_f32 v[32:35], v108, v20, v[32:35]
	v_mfma_f32_4x4x1_16b_f32 v[240:243], v109, v21, v[240:243]
	s_nop 0
	v_mfma_f32_4x4x1_16b_f32 v[32:35], v110, v22, v[32:35]
	v_mfma_f32_4x4x1_16b_f32 v[240:243], v111, v23, v[240:243]
	s_nop 0
	v_mfma_f32_4x4x1_16b_f32 v[32:35], v112, v24, v[32:35]
	v_mfma_f32_4x4x1_16b_f32 v[240:243], v113, v25, v[240:243]
	s_nop 0
	v_mfma_f32_4x4x1_16b_f32 v[32:35], v114, v26, v[32:35]
	v_mfma_f32_4x4x1_16b_f32 v[240:243], v115, v27, v[240:243]
	s_nop 0
	v_mfma_f32_4x4x1_16b_f32 v[32:35], v116, v28, v[32:35]
	v_mfma_f32_4x4x1_16b_f32 v[240:243], v117, v29, v[240:243]
	s_nop 0
	v_mfma_f32_4x4x1_16b_f32 v[32:35], v118, v30, v[32:35]
	v_mfma_f32_4x4x1_16b_f32 v[240:243], v119, v31, v[240:243]
	s_nop 0
	s_nop 3
	v_pk_add_f32 v[32:33], v[32:33], v[240:241]
	v_pk_add_f32 v[34:35], v[34:35], v[242:243]
	ds_read_b128 v[104:107], v234 offset:9856
	ds_read_b128 v[108:111], v234 offset:9872
	ds_read_b128 v[112:115], v234 offset:9888
	ds_read_b128 v[116:119], v234 offset:9904
	s_waitcnt lgkmcnt(8)
	s_nop 3
	v_mfma_f32_4x4x1_16b_f32 v[32:35], v120, v32, v[32:35]
	s_nop 3
	v_mfma_f32_4x4x1_16b_f32 v[32:35], v121, v33, v[32:35]
	s_nop 3
	v_mfma_f32_4x4x1_16b_f32 v[32:35], v122, v34, v[32:35]
	ds_read_b128 v[120:123], v234 offset:9920
	ds_read_b128 v[124:127], v234 offset:9936
	s_waitcnt lgkmcnt(6)
	s_nop 4
	v_mfma_f32_4x4x1_16b_f32 v[36:39], v88, v0, v[36:39]
	v_mfma_f32_4x4x1_16b_f32 v[240:243], v89, v1, 0
	s_nop 0
	v_mfma_f32_4x4x1_16b_f32 v[36:39], v90, v2, v[36:39]
	v_mfma_f32_4x4x1_16b_f32 v[240:243], v91, v3, v[240:243]
	s_nop 0
	v_mfma_f32_4x4x1_16b_f32 v[36:39], v92, v4, v[36:39]
	v_mfma_f32_4x4x1_16b_f32 v[240:243], v93, v5, v[240:243]
	s_nop 0
	v_mfma_f32_4x4x1_16b_f32 v[36:39], v94, v6, v[36:39]
	v_mfma_f32_4x4x1_16b_f32 v[240:243], v95, v7, v[240:243]
	s_nop 0
	v_mfma_f32_4x4x1_16b_f32 v[36:39], v96, v8, v[36:39]
	v_mfma_f32_4x4x1_16b_f32 v[240:243], v97, v9, v[240:243]
	s_nop 0
	v_mfma_f32_4x4x1_16b_f32 v[36:39], v98, v10, v[36:39]
	v_mfma_f32_4x4x1_16b_f32 v[240:243], v99, v11, v[240:243]
	s_nop 0
	v_mfma_f32_4x4x1_16b_f32 v[36:39], v100, v12, v[36:39]
	v_mfma_f32_4x4x1_16b_f32 v[240:243], v101, v13, v[240:243]
	s_nop 0
	v_mfma_f32_4x4x1_16b_f32 v[36:39], v102, v14, v[36:39]
	v_mfma_f32_4x4x1_16b_f32 v[240:243], v103, v15, v[240:243]
	s_nop 0
	ds_read_b128 v[88:91], v234 offset:10880
	ds_read_b128 v[92:95], v234 offset:10896
	ds_read_b128 v[96:99], v234 offset:10912
	ds_read_b128 v[100:103], v234 offset:10928
	s_waitcnt lgkmcnt(6)
; #define LAS __attribute__((address_space(3)))
; __device__ __forceinline__ void dn_prep_item(const Args& a, LAS unsigned char* lds, int item, int tid, int wave, int lane, int& cwh, int next_item) {
;     ...
;         { const LAS float* lrow = Lm + (lane & 15);
; #pragma unroll
;         for (int i = 1; i < 64; ++i) { float sa[4] = { x[i], 0.f, 0.f, 0.f };
;             int lr[4];
; #pragma unroll
;             for (int g = 0; g < (i + 15) / 16; ++g) lr[g] = __float_as_int(lrow[i * 68 + 16 * g]);
; #pragma unroll
;             for (int j = 0; j < i; ++j) { fmac_rowbcast_sel(sa[j & 3], lr[j >> 4], x[j], j); }
;             x[i] = (sa[0] + sa[1]) + (sa[2] + sa[3]); } }
	v_mfma_f32_4x4x1_16b_f32 v[36:39], v104, v16, v[36:39]
	v_mfma_f32_4x4x1_16b_f32 v[240:243], v105, v17, v[240:243]
	s_nop 0
	v_mfma_f32_4x4x1_16b_f32 v[36:39], v106, v18, v[36:39]
	v_mfma_f32_4x4x1_16b_f32 v[240:243], v107, v19, v[240:243]
	s_nop 0
	v_mfma_f32_4x4x1_16b_f32 v[36:39], v108, v20, v[36:39]
	v_mfma_f32_4x4x1_16b_f32 v[240:243], v109, v21, v[240:243]
	s_nop 0
	v_mfma_f32_4x4x1_16b_f32 v[36:39], v110, v22, v[36:39]
	v_mfma_f32_4x4x1_16b_f32 v[240:243], v111, v23, v[240:243]
	s_nop 0
	v_mfma_f32_4x4x1_16b_f32 v[36:39], v112, v24, v[36:39]
	v_mfma_f32_4x4x1_16b_f32 v[240:243], v113, v25, v[240:243]
	s_nop 0
	v_mfma_f32_4x4x1_16b_f32 v[36:39], v114, v26, v[36:39]
	v_mfma_f32_4x4x1_16b_f32 v[240:243], v115, v27, v[240:243]
	s_nop 0
	v_mfma_f32_4x4x1_16b_f32 v[36:39], v116, v28, v[36:39]
	v_mfma_f32_4x4x1_16b_f32 v[240:243], v117, v29, v[240:243]
	s_nop 0
	v_mfma_f32_4x4x1_16b_f32 v[36:39], v118, v30, v[36:39]
	v_mfma_f32_4x4x1_16b_f32 v[240:243], v119, v31, v[240:243]
	s_nop 0
	ds_read_b128 v[104:107], v234 offset:10944
	ds_read_b128 v[108:111], v234 offset:10960
	ds_read_b128 v[112:115], v234 offset:10976
	ds_read_b128 v[116:119], v234 offset:10992
	s_waitcnt lgkmcnt(8)
	v_mfma_f32_4x4x1_16b_f32 v[36:39], v120, v32, v[36:39]
	v_mfma_f32_4x4x1_16b_f32 v[240:243], v121, v33, v[240:243]
	s_nop 0
	v_mfma_f32_4x4x1_16b_f32 v[36:39], v122, v34, v[36:39]
	v_mfma_f32_4x4x1_16b_f32 v[240:243], v123, v35, v[240:243]
	s_nop 0
	s_nop 3
	v_pk_add_f32 v[36:37], v[36:37], v[240:241]
	v_pk_add_f32 v[38:39], v[38:39], v[242:243]
	s_nop 3
	v_mfma_f32_4x4x1_16b_f32 v[36:39], v124, v36, v[36:39]
	s_nop 3
	v_mfma_f32_4x4x1_16b_f32 v[36:39], v125, v37, v[36:39]
	s_nop 3
	v_mfma_f32_4x4x1_16b_f32 v[36:39], v126, v38, v[36:39]
	ds_read_b128 v[120:123], v234 offset:11008
	ds_read_b128 v[124:127], v234 offset:11024
	ds_read_b128 v[128:131], v234 offset:11040
	s_waitcnt lgkmcnt(7)
	s_nop 4
	v_mfma_f32_4x4x1_16b_f32 v[40:43], v88, v0, v[40:43]
	v_mfma_f32_4x4x1_16b_f32 v[240:243], v89, v1, 0
	s_nop 0
	v_mfma_f32_4x4x1_16b_f32 v[40:43], v90, v2, v[40:43]
	v_mfma_f32_4x4x1_16b_f32 v[240:243], v91, v3, v[240:243]
	s_nop 0
	v_mfma_f32_4x4x1_16b_f32 v[40:43], v92, v4, v[40:43]
	v_mfma_f32_4x4x1_16b_f32 v[240:243], v93, v5, v[240:243]
	s_nop 0
	v_mfma_f32_4x4x1_16b_f32 v[40:43], v94, v6, v[40:43]
	v_mfma_f32_4x4x1_16b_f32 v[240:243], v95, v7, v[240:243]
	s_nop 0
	v_mfma_f32_4x4x1_16b_f32 v[40:43], v96, v8, v[40:43]
	v_mfma_f32_4x4x1_16b_f32 v[240:243], v97, v9, v[240:243]
	s_nop 0
	v_mfma_f32_4x4x1_16b_f32 v[40:43], v98, v10, v[40:43]
	v_mfma_f32_4x4x1_16b_f32 v[240:243], v99, v11, v[240:243]
	s_nop 0
	v_mfma_f32_4x4x1_16b_f32 v[40:43], v100, v12, v[40:43]
	v_mfma_f32_4x4x1_16b_f32 v[240:243], v101, v13, v[240:243]
	s_nop 0
	v_mfma_f32_4x4x1_16b_f32 v[40:43], v102, v14, v[40:43]
	v_mfma_f32_4x4x1_16b_f32 v[240:243], v103, v15, v[240:243]
	s_nop 0
	ds_read_b128 v[88:91], v234 offset:11968
	ds_read_b128 v[92:95], v234 offset:11984
	ds_read_b128 v[96:99], v234 offset:12000
	ds_read_b128 v[100:103], v234 offset:12016
	s_waitcnt lgkmcnt(7)
	v_mfma_f32_4x4x1_16b_f32 v[40:43], v104, v16, v[40:43]
	v_mfma_f32_4x4x1_16b_f32 v[240:243], v105, v17, v[240:243]
	s_nop 0
	v_mfma_f32_4x4x1_16b_f32 v[40:43], v106, v18, v[40:43]
	v_mfma_f32_4x4x1_16b_f32 v[240:243], v107, v19, v[240:243]
	s_nop 0
	v_mfma_f32_4x4x1_16b_f32 v[40:43], v108, v20, v[40:43]
	v_mfma_f32_4x4x1_16b_f32 v[240:243], v109, v21, v[240:243]
	s_nop 0
	v_mfma_f32_4x4x1_16b_f32 v[40:43], v110, v22, v[40:43]
	v_mfma_f32_4x4x1_16b_f32 v[240:243], v111, v23, v[240:243]
	s_nop 0
	v_mfma_f32_4x4x1_16b_f32 v[40:43], v112, v24, v[40:43]
	v_mfma_f32_4x4x1_16b_f32 v[240:243], v113, v25, v[240:243]
	s_nop 0
	v_mfma_f32_4x4x1_16b_f32 v[40:43], v114, v26, v[40:43]
	v_mfma_f32_4x4x1_16b_f32 v[240:243], v115, v27, v[240:243]
	s_nop 0
	v_mfma_f32_4x4x1_16b_f32 v[40:43], v116, v28, v[40:43]
	v_mfma_f32_4x4x1_16b_f32 v[240:243], v117, v29, v[240:243]
	s_nop 0
	v_mfma_f32_4x4x1_16b_f32 v[40:43], v118, v30, v[40:43]
	v_mfma_f32_4x4x1_16b_f32 v[240:243], v119, v31, v[240:243]
	s_nop 0
	ds_read_b128 v[104:107], v234 offset:12032
	ds_read_b128 v[108:111], v234 offset:12048
	ds_read_b128 v[112:115], v234 offset:12064
	ds_read_b128 v[116:119], v234 offset:12080
	s_waitcnt lgkmcnt(8)
	v_mfma_f32_4x4x1_16b_f32 v[40:43], v120, v32, v[40:43]
	v_mfma_f32_4x4x1_16b_f32 v[240:243], v121, v33, v[240:243]
	s_nop 0
	v_mfma_f32_4x4x1_16b_f32 v[40:43], v122, v34, v[40:43]
	v_mfma_f32_4x4x1_16b_f32 v[240:243], v123, v35, v[240:243]
	s_nop 0
	v_mfma_f32_4x4x1_16b_f32 v[40:43], v124, v36, v[40:43]
	v_mfma_f32_4x4x1_16b_f32 v[240:243], v125, v37, v[240:243]
	s_nop 0
	v_mfma_f32_4x4x1_16b_f32 v[40:43], v126, v38, v[40:43]
	v_mfma_f32_4x4x1_16b_f32 v[240:243], v127, v39, v[240:243]
	s_nop 0
	s_nop 3
	v_pk_add_f32 v[40:41], v[40:41], v[240:241]
	v_pk_add_f32 v[42:43], v[42:43], v[242:243]
	s_nop 3
	v_mfma_f32_4x4x1_16b_f32 v[40:43], v128, v40, v[40:43]
	s_nop 3
	v_mfma_f32_4x4x1_16b_f32 v[40:43], v129, v41, v[40:43]
	s_nop 3
	v_mfma_f32_4x4x1_16b_f32 v[40:43], v130, v42, v[40:43]
	ds_read_b128 v[120:123], v234 offset:12096
	ds_read_b128 v[124:127], v234 offset:12112
	ds_read_b128 v[128:131], v234 offset:12128
	ds_read_b128 v[132:135], v234 offset:12144
	s_waitcnt lgkmcnt(8)
; #define LAS __attribute__((address_space(3)))
; __device__ __forceinline__ void dn_prep_item(const Args& a, LAS unsigned char* lds, int item, int tid, int wave, int lane, int& cwh, int next_item) {
;     ...
;         { const LAS float* lrow = Lm + (lane & 15);
; #pragma unroll
;         for (int i = 1; i < 64; ++i) { float sa[4] = { x[i], 0.f, 0.f, 0.f };
;             int lr[4];
; #pragma unroll
;             for (int g = 0; g < (i + 15) / 16; ++g) lr[g] = __float_as_int(lrow[i * 68 + 16 * g]);
; #pragma unroll
;             for (int j = 0; j < i; ++j) { fmac_rowbcast_sel(sa[j & 3], lr[j >> 4], x[j], j); }
;             x[i] = (sa[0] + sa[1]) + (sa[2] + sa[3]); } }
	s_nop 4
	v_mfma_f32_4x4x1_16b_f32 v[44:47], v88, v0, v[44:47]
	v_mfma_f32_4x4x1_16b_f32 v[240:243], v89, v1, 0
	s_nop 0
	v_mfma_f32_4x4x1_16b_f32 v[44:47], v90, v2, v[44:47]
	v_mfma_f32_4x4x1_16b_f32 v[240:243], v91, v3, v[240:243]
	s_nop 0
	v_mfma_f32_4x4x1_16b_f32 v[44:47], v92, v4, v[44:47]
	v_mfma_f32_4x4x1_16b_f32 v[240:243], v93, v5, v[240:243]
	s_nop 0
	v_mfma_f32_4x4x1_16b_f32 v[44:47], v94, v6, v[44:47]
	v_mfma_f32_4x4x1_16b_f32 v[240:243], v95, v7, v[240:243]
	s_nop 0
	v_mfma_f32_4x4x1_16b_f32 v[44:47], v96, v8, v[44:47]
	v_mfma_f32_4x4x1_16b_f32 v[240:243], v97, v9, v[240:243]
	s_nop 0
	v_mfma_f32_4x4x1_16b_f32 v[44:47], v98, v10, v[44:47]
	v_mfma_f32_4x4x1_16b_f32 v[240:243], v99, v11, v[240:243]
	s_nop 0
	v_mfma_f32_4x4x1_16b_f32 v[44:47], v100, v12, v[44:47]
	v_mfma_f32_4x4x1_16b_f32 v[240:243], v101, v13, v[240:243]
	s_nop 0
	v_mfma_f32_4x4x1_16b_f32 v[44:47], v102, v14, v[44:47]
	v_mfma_f32_4x4x1_16b_f32 v[240:243], v103, v15, v[240:243]
	s_nop 0
	ds_read_b128 v[88:91], v234 offset:13056
	ds_read_b128 v[92:95], v234 offset:13072
	ds_read_b128 v[96:99], v234 offset:13088
	ds_read_b128 v[100:103], v234 offset:13104
	s_waitcnt lgkmcnt(8)
	v_mfma_f32_4x4x1_16b_f32 v[44:47], v104, v16, v[44:47]
	v_mfma_f32_4x4x1_16b_f32 v[240:243], v105, v17, v[240:243]
	s_nop 0
	v_mfma_f32_4x4x1_16b_f32 v[44:47], v106, v18, v[44:47]
	v_mfma_f32_4x4x1_16b_f32 v[240:243], v107, v19, v[240:243]
	s_nop 0
	v_mfma_f32_4x4x1_16b_f32 v[44:47], v108, v20, v[44:47]
	v_mfma_f32_4x4x1_16b_f32 v[240:243], v109, v21, v[240:243]
	s_nop 0
	v_mfma_f32_4x4x1_16b_f32 v[44:47], v110, v22, v[44:47]
	v_mfma_f32_4x4x1_16b_f32 v[240:243], v111, v23, v[240:243]
	s_nop 0
	v_mfma_f32_4x4x1_16b_f32 v[44:47], v112, v24, v[44:47]
	v_mfma_f32_4x4x1_16b_f32 v[240:243], v113, v25, v[240:243]
	s_nop 0
	v_mfma_f32_4x4x1_16b_f32 v[44:47], v114, v26, v[44:47]
	v_mfma_f32_4x4x1_16b_f32 v[240:243], v115, v27, v[240:243]
	s_nop 0
	v_mfma_f32_4x4x1_16b_f32 v[44:47], v116, v28, v[44:47]
	v_mfma_f32_4x4x1_16b_f32 v[240:243], v117, v29, v[240:243]
	s_nop 0
	v_mfma_f32_4x4x1_16b_f32 v[44:47], v118, v30, v[44:47]
	v_mfma_f32_4x4x1_16b_f32 v[240:243], v119, v31, v[240:243]
	s_nop 0
	ds_read_b128 v[104:107], v234 offset:13120
	ds_read_b128 v[108:111], v234 offset:13136
	ds_read_b128 v[112:115], v234 offset:13152
	ds_read_b128 v[116:119], v234 offset:13168
	s_waitcnt lgkmcnt(8)
	v_mfma_f32_4x4x1_16b_f32 v[44:47], v120, v32, v[44:47]
	v_mfma_f32_4x4x1_16b_f32 v[240:243], v121, v33, v[240:243]
	s_nop 0
	v_mfma_f32_4x4x1_16b_f32 v[44:47], v122, v34, v[44:47]
	v_mfma_f32_4x4x1_16b_f32 v[240:243], v123, v35, v[240:243]
	s_nop 0
	v_mfma_f32_4x4x1_16b_f32 v[44:47], v124, v36, v[44:47]
	v_mfma_f32_4x4x1_16b_f32 v[240:243], v125, v37, v[240:243]
	s_nop 0
	v_mfma_f32_4x4x1_16b_f32 v[44:47], v126, v38, v[44:47]
	v_mfma_f32_4x4x1_16b_f32 v[240:243], v127, v39, v[240:243]
	s_nop 0
	v_mfma_f32_4x4x1_16b_f32 v[44:47], v128, v40, v[44:47]
	v_mfma_f32_4x4x1_16b_f32 v[240:243], v129, v41, v[240:243]
	s_nop 0
	v_mfma_f32_4x4x1_16b_f32 v[44:47], v130, v42, v[44:47]
	v_mfma_f32_4x4x1_16b_f32 v[240:243], v131, v43, v[240:243]
	s_nop 0
	s_nop 3
	v_pk_add_f32 v[44:45], v[44:45], v[240:241]
	v_pk_add_f32 v[46:47], v[46:47], v[242:243]
	s_nop 3
	v_mfma_f32_4x4x1_16b_f32 v[44:47], v132, v44, v[44:47]
	s_nop 3
	v_mfma_f32_4x4x1_16b_f32 v[44:47], v133, v45, v[44:47]
	s_nop 3
	v_mfma_f32_4x4x1_16b_f32 v[44:47], v134, v46, v[44:47]
	ds_read_b128 v[120:123], v234 offset:13184
	ds_read_b128 v[124:127], v234 offset:13200
	ds_read_b128 v[128:131], v234 offset:13216
	ds_read_b128 v[132:135], v234 offset:13232
	s_waitcnt lgkmcnt(8)
	s_nop 4
	v_mfma_f32_4x4x1_16b_f32 v[72:75], v88, v0, v[72:75]
	v_mfma_f32_4x4x1_16b_f32 v[240:243], v89, v1, 0
	s_nop 0
	v_mfma_f32_4x4x1_16b_f32 v[72:75], v90, v2, v[72:75]
	v_mfma_f32_4x4x1_16b_f32 v[240:243], v91, v3, v[240:243]
	s_nop 0
	v_mfma_f32_4x4x1_16b_f32 v[72:75], v92, v4, v[72:75]
	v_mfma_f32_4x4x1_16b_f32 v[240:243], v93, v5, v[240:243]
	s_nop 0
	v_mfma_f32_4x4x1_16b_f32 v[72:75], v94, v6, v[72:75]
	v_mfma_f32_4x4x1_16b_f32 v[240:243], v95, v7, v[240:243]
	s_nop 0
	v_mfma_f32_4x4x1_16b_f32 v[72:75], v96, v8, v[72:75]
	v_mfma_f32_4x4x1_16b_f32 v[240:243], v97, v9, v[240:243]
	s_nop 0
	v_mfma_f32_4x4x1_16b_f32 v[72:75], v98, v10, v[72:75]
	v_mfma_f32_4x4x1_16b_f32 v[240:243], v99, v11, v[240:243]
	s_nop 0
	v_mfma_f32_4x4x1_16b_f32 v[72:75], v100, v12, v[72:75]
	v_mfma_f32_4x4x1_16b_f32 v[240:243], v101, v13, v[240:243]
	s_nop 0
	v_mfma_f32_4x4x1_16b_f32 v[72:75], v102, v14, v[72:75]
	v_mfma_f32_4x4x1_16b_f32 v[240:243], v103, v15, v[240:243]
	s_nop 0
	ds_read_b128 v[88:91], v234 offset:13248
	s_waitcnt lgkmcnt(5)
	v_mfma_f32_4x4x1_16b_f32 v[72:75], v104, v16, v[72:75]
	v_mfma_f32_4x4x1_16b_f32 v[240:243], v105, v17, v[240:243]
	s_nop 0
	v_mfma_f32_4x4x1_16b_f32 v[72:75], v106, v18, v[72:75]
	v_mfma_f32_4x4x1_16b_f32 v[240:243], v107, v19, v[240:243]
	s_nop 0
	v_mfma_f32_4x4x1_16b_f32 v[72:75], v108, v20, v[72:75]
	v_mfma_f32_4x4x1_16b_f32 v[240:243], v109, v21, v[240:243]
	s_nop 0
	v_mfma_f32_4x4x1_16b_f32 v[72:75], v110, v22, v[72:75]
	v_mfma_f32_4x4x1_16b_f32 v[240:243], v111, v23, v[240:243]
	s_nop 0
	v_mfma_f32_4x4x1_16b_f32 v[72:75], v112, v24, v[72:75]
	v_mfma_f32_4x4x1_16b_f32 v[240:243], v113, v25, v[240:243]
	s_nop 0
	v_mfma_f32_4x4x1_16b_f32 v[72:75], v114, v26, v[72:75]
	v_mfma_f32_4x4x1_16b_f32 v[240:243], v115, v27, v[240:243]
	s_nop 0
	v_mfma_f32_4x4x1_16b_f32 v[72:75], v116, v28, v[72:75]
	v_mfma_f32_4x4x1_16b_f32 v[240:243], v117, v29, v[240:243]
	s_nop 0
	v_mfma_f32_4x4x1_16b_f32 v[72:75], v118, v30, v[72:75]
	v_mfma_f32_4x4x1_16b_f32 v[240:243], v119, v31, v[240:243]
	s_nop 0
	ds_read_b128 v[104:107], v234 offset:14144
	ds_read_b128 v[108:111], v234 offset:14160
	ds_read_b128 v[112:115], v234 offset:14176
	ds_read_b128 v[116:119], v234 offset:14192
	s_waitcnt lgkmcnt(5)
; #define LAS __attribute__((address_space(3)))
; __device__ __forceinline__ void dn_prep_item(const Args& a, LAS unsigned char* lds, int item, int tid, int wave, int lane, int& cwh, int next_item) {
;     ...
;         { const LAS float* lrow = Lm + (lane & 15);
; #pragma unroll
;         for (int i = 1; i < 64; ++i) { float sa[4] = { x[i], 0.f, 0.f, 0.f };
;             int lr[4];
; #pragma unroll
;             for (int g = 0; g < (i + 15) / 16; ++g) lr[g] = __float_as_int(lrow[i * 68 + 16 * g]);
; #pragma unroll
;             for (int j = 0; j < i; ++j) { fmac_rowbcast_sel(sa[j & 3], lr[j >> 4], x[j], j); }
;             x[i] = (sa[0] + sa[1]) + (sa[2] + sa[3]); } }
	v_mfma_f32_4x4x1_16b_f32 v[72:75], v120, v32, v[72:75]
	v_mfma_f32_4x4x1_16b_f32 v[240:243], v121, v33, v[240:243]
	s_nop 0
	v_mfma_f32_4x4x1_16b_f32 v[72:75], v122, v34, v[72:75]
	v_mfma_f32_4x4x1_16b_f32 v[240:243], v123, v35, v[240:243]
	s_nop 0
	v_mfma_f32_4x4x1_16b_f32 v[72:75], v124, v36, v[72:75]
	v_mfma_f32_4x4x1_16b_f32 v[240:243], v125, v37, v[240:243]
	s_nop 0
	v_mfma_f32_4x4x1_16b_f32 v[72:75], v126, v38, v[72:75]
	v_mfma_f32_4x4x1_16b_f32 v[240:243], v127, v39, v[240:243]
	s_nop 0
	v_mfma_f32_4x4x1_16b_f32 v[72:75], v128, v40, v[72:75]
	v_mfma_f32_4x4x1_16b_f32 v[240:243], v129, v41, v[240:243]
	s_nop 0
	v_mfma_f32_4x4x1_16b_f32 v[72:75], v130, v42, v[72:75]
	v_mfma_f32_4x4x1_16b_f32 v[240:243], v131, v43, v[240:243]
	s_nop 0
	v_mfma_f32_4x4x1_16b_f32 v[72:75], v132, v44, v[72:75]
	v_mfma_f32_4x4x1_16b_f32 v[240:243], v133, v45, v[240:243]
	s_nop 0
	v_mfma_f32_4x4x1_16b_f32 v[72:75], v134, v46, v[72:75]
	v_mfma_f32_4x4x1_16b_f32 v[240:243], v135, v47, v[240:243]
	s_nop 0
	s_nop 3
	v_pk_add_f32 v[72:73], v[72:73], v[240:241]
	v_pk_add_f32 v[74:75], v[74:75], v[242:243]
	ds_read_b128 v[120:123], v234 offset:14208
	ds_read_b128 v[124:127], v234 offset:14224
	ds_read_b128 v[128:131], v234 offset:14240
	ds_read_b128 v[132:135], v234 offset:14256
	s_waitcnt lgkmcnt(8)
	s_nop 3
	v_mfma_f32_4x4x1_16b_f32 v[72:75], v88, v72, v[72:75]
	s_nop 3
	v_mfma_f32_4x4x1_16b_f32 v[72:75], v89, v73, v[72:75]
	s_nop 3
	v_mfma_f32_4x4x1_16b_f32 v[72:75], v90, v74, v[72:75]
	ds_read_b128 v[88:91], v234 offset:14272
	ds_read_b128 v[92:95], v234 offset:14288
	ds_read_b128 v[96:99], v234 offset:14304
	ds_read_b128 v[100:103], v234 offset:14320
	s_waitcnt lgkmcnt(8)
	s_nop 4
	v_mfma_f32_4x4x1_16b_f32 v[76:79], v104, v0, v[76:79]
	v_mfma_f32_4x4x1_16b_f32 v[240:243], v105, v1, 0
	s_nop 0
	v_mfma_f32_4x4x1_16b_f32 v[76:79], v106, v2, v[76:79]
	v_mfma_f32_4x4x1_16b_f32 v[240:243], v107, v3, v[240:243]
	s_nop 0
	v_mfma_f32_4x4x1_16b_f32 v[76:79], v108, v4, v[76:79]
	v_mfma_f32_4x4x1_16b_f32 v[240:243], v109, v5, v[240:243]
	s_nop 0
	v_mfma_f32_4x4x1_16b_f32 v[76:79], v110, v6, v[76:79]
	v_mfma_f32_4x4x1_16b_f32 v[240:243], v111, v7, v[240:243]
	s_nop 0
	v_mfma_f32_4x4x1_16b_f32 v[76:79], v112, v8, v[76:79]
	v_mfma_f32_4x4x1_16b_f32 v[240:243], v113, v9, v[240:243]
	s_nop 0
	v_mfma_f32_4x4x1_16b_f32 v[76:79], v114, v10, v[76:79]
	v_mfma_f32_4x4x1_16b_f32 v[240:243], v115, v11, v[240:243]
	s_nop 0
	v_mfma_f32_4x4x1_16b_f32 v[76:79], v116, v12, v[76:79]
	v_mfma_f32_4x4x1_16b_f32 v[240:243], v117, v13, v[240:243]
	s_nop 0
	v_mfma_f32_4x4x1_16b_f32 v[76:79], v118, v14, v[76:79]
	v_mfma_f32_4x4x1_16b_f32 v[240:243], v119, v15, v[240:243]
	s_nop 0
	ds_read_b128 v[104:107], v234 offset:14336
	ds_read_b128 v[108:111], v234 offset:14352
	s_waitcnt lgkmcnt(6)
	v_mfma_f32_4x4x1_16b_f32 v[76:79], v120, v16, v[76:79]
	v_mfma_f32_4x4x1_16b_f32 v[240:243], v121, v17, v[240:243]
	s_nop 0
	v_mfma_f32_4x4x1_16b_f32 v[76:79], v122, v18, v[76:79]
	v_mfma_f32_4x4x1_16b_f32 v[240:243], v123, v19, v[240:243]
	s_nop 0
	v_mfma_f32_4x4x1_16b_f32 v[76:79], v124, v20, v[76:79]
	v_mfma_f32_4x4x1_16b_f32 v[240:243], v125, v21, v[240:243]
	s_nop 0
	v_mfma_f32_4x4x1_16b_f32 v[76:79], v126, v22, v[76:79]
	v_mfma_f32_4x4x1_16b_f32 v[240:243], v127, v23, v[240:243]
	s_nop 0
	v_mfma_f32_4x4x1_16b_f32 v[76:79], v128, v24, v[76:79]
	v_mfma_f32_4x4x1_16b_f32 v[240:243], v129, v25, v[240:243]
	s_nop 0
	v_mfma_f32_4x4x1_16b_f32 v[76:79], v130, v26, v[76:79]
	v_mfma_f32_4x4x1_16b_f32 v[240:243], v131, v27, v[240:243]
	s_nop 0
	v_mfma_f32_4x4x1_16b_f32 v[76:79], v132, v28, v[76:79]
	v_mfma_f32_4x4x1_16b_f32 v[240:243], v133, v29, v[240:243]
	s_nop 0
	v_mfma_f32_4x4x1_16b_f32 v[76:79], v134, v30, v[76:79]
	v_mfma_f32_4x4x1_16b_f32 v[240:243], v135, v31, v[240:243]
	s_nop 0
	ds_read_b128 v[120:123], v234 offset:15232
	ds_read_b128 v[124:127], v234 offset:15248
	ds_read_b128 v[128:131], v234 offset:15264
	ds_read_b128 v[132:135], v234 offset:15280
	s_waitcnt lgkmcnt(6)
	v_mfma_f32_4x4x1_16b_f32 v[76:79], v88, v32, v[76:79]
	v_mfma_f32_4x4x1_16b_f32 v[240:243], v89, v33, v[240:243]
	s_nop 0
	v_mfma_f32_4x4x1_16b_f32 v[76:79], v90, v34, v[76:79]
	v_mfma_f32_4x4x1_16b_f32 v[240:243], v91, v35, v[240:243]
	s_nop 0
	v_mfma_f32_4x4x1_16b_f32 v[76:79], v92, v36, v[76:79]
	v_mfma_f32_4x4x1_16b_f32 v[240:243], v93, v37, v[240:243]
	s_nop 0
	v_mfma_f32_4x4x1_16b_f32 v[76:79], v94, v38, v[76:79]
	v_mfma_f32_4x4x1_16b_f32 v[240:243], v95, v39, v[240:243]
	s_nop 0
	v_mfma_f32_4x4x1_16b_f32 v[76:79], v96, v40, v[76:79]
	v_mfma_f32_4x4x1_16b_f32 v[240:243], v97, v41, v[240:243]
	s_nop 0
	v_mfma_f32_4x4x1_16b_f32 v[76:79], v98, v42, v[76:79]
	v_mfma_f32_4x4x1_16b_f32 v[240:243], v99, v43, v[240:243]
	s_nop 0
	v_mfma_f32_4x4x1_16b_f32 v[76:79], v100, v44, v[76:79]
	v_mfma_f32_4x4x1_16b_f32 v[240:243], v101, v45, v[240:243]
	s_nop 0
	v_mfma_f32_4x4x1_16b_f32 v[76:79], v102, v46, v[76:79]
	v_mfma_f32_4x4x1_16b_f32 v[240:243], v103, v47, v[240:243]
	s_nop 0
	ds_read_b128 v[88:91], v234 offset:15296
	ds_read_b128 v[92:95], v234 offset:15312
	ds_read_b128 v[96:99], v234 offset:15328
	ds_read_b128 v[100:103], v234 offset:15344
	s_waitcnt lgkmcnt(8)
	v_mfma_f32_4x4x1_16b_f32 v[76:79], v104, v72, v[76:79]
	v_mfma_f32_4x4x1_16b_f32 v[240:243], v105, v73, v[240:243]
	s_nop 0
	v_mfma_f32_4x4x1_16b_f32 v[76:79], v106, v74, v[76:79]
	v_mfma_f32_4x4x1_16b_f32 v[240:243], v107, v75, v[240:243]
	s_nop 0
	s_nop 3
	v_pk_add_f32 v[76:77], v[76:77], v[240:241]
	v_pk_add_f32 v[78:79], v[78:79], v[242:243]
	s_nop 3
	v_mfma_f32_4x4x1_16b_f32 v[76:79], v108, v76, v[76:79]
	s_nop 3
	v_mfma_f32_4x4x1_16b_f32 v[76:79], v109, v77, v[76:79]
	s_nop 3
	v_mfma_f32_4x4x1_16b_f32 v[76:79], v110, v78, v[76:79]
	ds_read_b128 v[104:107], v234 offset:15360
	ds_read_b128 v[108:111], v234 offset:15376
	ds_read_b128 v[112:115], v234 offset:15392
	ds_read_b128 v[116:119], v234 offset:15408
	s_waitcnt lgkmcnt(8)
; #define LAS __attribute__((address_space(3)))
; __device__ __forceinline__ void dn_prep_item(const Args& a, LAS unsigned char* lds, int item, int tid, int wave, int lane, int& cwh, int next_item) {
;     ...
;         { const LAS float* lrow = Lm + (lane & 15);
; #pragma unroll
;         for (int i = 1; i < 64; ++i) { float sa[4] = { x[i], 0.f, 0.f, 0.f };
;             int lr[4];
; #pragma unroll
;             for (int g = 0; g < (i + 15) / 16; ++g) lr[g] = __float_as_int(lrow[i * 68 + 16 * g]);
; #pragma unroll
;             for (int j = 0; j < i; ++j) { fmac_rowbcast_sel(sa[j & 3], lr[j >> 4], x[j], j); }
;             x[i] = (sa[0] + sa[1]) + (sa[2] + sa[3]); } }
	s_nop 4
	v_mfma_f32_4x4x1_16b_f32 v[80:83], v120, v0, v[80:83]
	v_mfma_f32_4x4x1_16b_f32 v[240:243], v121, v1, 0
	s_nop 0
	v_mfma_f32_4x4x1_16b_f32 v[80:83], v122, v2, v[80:83]
	v_mfma_f32_4x4x1_16b_f32 v[240:243], v123, v3, v[240:243]
	s_nop 0
	v_mfma_f32_4x4x1_16b_f32 v[80:83], v124, v4, v[80:83]
	v_mfma_f32_4x4x1_16b_f32 v[240:243], v125, v5, v[240:243]
	s_nop 0
	v_mfma_f32_4x4x1_16b_f32 v[80:83], v126, v6, v[80:83]
	v_mfma_f32_4x4x1_16b_f32 v[240:243], v127, v7, v[240:243]
	s_nop 0
	v_mfma_f32_4x4x1_16b_f32 v[80:83], v128, v8, v[80:83]
	v_mfma_f32_4x4x1_16b_f32 v[240:243], v129, v9, v[240:243]
	s_nop 0
	v_mfma_f32_4x4x1_16b_f32 v[80:83], v130, v10, v[80:83]
	v_mfma_f32_4x4x1_16b_f32 v[240:243], v131, v11, v[240:243]
	s_nop 0
	v_mfma_f32_4x4x1_16b_f32 v[80:83], v132, v12, v[80:83]
	v_mfma_f32_4x4x1_16b_f32 v[240:243], v133, v13, v[240:243]
	s_nop 0
	v_mfma_f32_4x4x1_16b_f32 v[80:83], v134, v14, v[80:83]
	v_mfma_f32_4x4x1_16b_f32 v[240:243], v135, v15, v[240:243]
	s_nop 0
	ds_read_b128 v[120:123], v234 offset:15424
	ds_read_b128 v[124:127], v234 offset:15440
	ds_read_b128 v[128:131], v234 offset:15456
	s_waitcnt lgkmcnt(7)
	v_mfma_f32_4x4x1_16b_f32 v[80:83], v88, v16, v[80:83]
	v_mfma_f32_4x4x1_16b_f32 v[240:243], v89, v17, v[240:243]
	s_nop 0
	v_mfma_f32_4x4x1_16b_f32 v[80:83], v90, v18, v[80:83]
	v_mfma_f32_4x4x1_16b_f32 v[240:243], v91, v19, v[240:243]
	s_nop 0
	v_mfma_f32_4x4x1_16b_f32 v[80:83], v92, v20, v[80:83]
	v_mfma_f32_4x4x1_16b_f32 v[240:243], v93, v21, v[240:243]
	s_nop 0
	v_mfma_f32_4x4x1_16b_f32 v[80:83], v94, v22, v[80:83]
	v_mfma_f32_4x4x1_16b_f32 v[240:243], v95, v23, v[240:243]
	s_nop 0
	v_mfma_f32_4x4x1_16b_f32 v[80:83], v96, v24, v[80:83]
	v_mfma_f32_4x4x1_16b_f32 v[240:243], v97, v25, v[240:243]
	s_nop 0
	v_mfma_f32_4x4x1_16b_f32 v[80:83], v98, v26, v[80:83]
	v_mfma_f32_4x4x1_16b_f32 v[240:243], v99, v27, v[240:243]
	s_nop 0
	v_mfma_f32_4x4x1_16b_f32 v[80:83], v100, v28, v[80:83]
	v_mfma_f32_4x4x1_16b_f32 v[240:243], v101, v29, v[240:243]
	s_nop 0
	v_mfma_f32_4x4x1_16b_f32 v[80:83], v102, v30, v[80:83]
	v_mfma_f32_4x4x1_16b_f32 v[240:243], v103, v31, v[240:243]
	s_nop 0
	ds_read_b128 v[88:91], v234 offset:16320
	ds_read_b128 v[92:95], v234 offset:16336
	ds_read_b128 v[96:99], v234 offset:16352
	ds_read_b128 v[100:103], v234 offset:16368
	s_waitcnt lgkmcnt(7)
	v_mfma_f32_4x4x1_16b_f32 v[80:83], v104, v32, v[80:83]
	v_mfma_f32_4x4x1_16b_f32 v[240:243], v105, v33, v[240:243]
	s_nop 0
	v_mfma_f32_4x4x1_16b_f32 v[80:83], v106, v34, v[80:83]
	v_mfma_f32_4x4x1_16b_f32 v[240:243], v107, v35, v[240:243]
	s_nop 0
	v_mfma_f32_4x4x1_16b_f32 v[80:83], v108, v36, v[80:83]
	v_mfma_f32_4x4x1_16b_f32 v[240:243], v109, v37, v[240:243]
	s_nop 0
	v_mfma_f32_4x4x1_16b_f32 v[80:83], v110, v38, v[80:83]
	v_mfma_f32_4x4x1_16b_f32 v[240:243], v111, v39, v[240:243]
	s_nop 0
	v_mfma_f32_4x4x1_16b_f32 v[80:83], v112, v40, v[80:83]
	v_mfma_f32_4x4x1_16b_f32 v[240:243], v113, v41, v[240:243]
	s_nop 0
	v_mfma_f32_4x4x1_16b_f32 v[80:83], v114, v42, v[80:83]
	v_mfma_f32_4x4x1_16b_f32 v[240:243], v115, v43, v[240:243]
	s_nop 0
	v_mfma_f32_4x4x1_16b_f32 v[80:83], v116, v44, v[80:83]
	v_mfma_f32_4x4x1_16b_f32 v[240:243], v117, v45, v[240:243]
	s_nop 0
	v_mfma_f32_4x4x1_16b_f32 v[80:83], v118, v46, v[80:83]
	v_mfma_f32_4x4x1_16b_f32 v[240:243], v119, v47, v[240:243]
	s_nop 0
	ds_read_b128 v[104:107], v234 offset:16384
	ds_read_b128 v[108:111], v234 offset:16400
	ds_read_b128 v[112:115], v234 offset:16416
	ds_read_b128 v[116:119], v234 offset:16432
	s_waitcnt lgkmcnt(8)
	v_mfma_f32_4x4x1_16b_f32 v[80:83], v120, v72, v[80:83]
	v_mfma_f32_4x4x1_16b_f32 v[240:243], v121, v73, v[240:243]
	s_nop 0
	v_mfma_f32_4x4x1_16b_f32 v[80:83], v122, v74, v[80:83]
	v_mfma_f32_4x4x1_16b_f32 v[240:243], v123, v75, v[240:243]
	s_nop 0
	v_mfma_f32_4x4x1_16b_f32 v[80:83], v124, v76, v[80:83]
	v_mfma_f32_4x4x1_16b_f32 v[240:243], v125, v77, v[240:243]
	s_nop 0
	v_mfma_f32_4x4x1_16b_f32 v[80:83], v126, v78, v[80:83]
	v_mfma_f32_4x4x1_16b_f32 v[240:243], v127, v79, v[240:243]
	s_nop 0
	s_nop 3
	v_pk_add_f32 v[80:81], v[80:81], v[240:241]
	v_pk_add_f32 v[82:83], v[82:83], v[242:243]
	s_nop 3
	v_mfma_f32_4x4x1_16b_f32 v[80:83], v128, v80, v[80:83]
	s_nop 3
	v_mfma_f32_4x4x1_16b_f32 v[80:83], v129, v81, v[80:83]
	s_nop 3
	v_mfma_f32_4x4x1_16b_f32 v[80:83], v130, v82, v[80:83]
	ds_read_b128 v[120:123], v234 offset:16448
	ds_read_b128 v[124:127], v234 offset:16464
	ds_read_b128 v[128:131], v234 offset:16480
	ds_read_b128 v[132:135], v234 offset:16496
	s_waitcnt lgkmcnt(8)
	s_nop 4
	v_mfma_f32_4x4x1_16b_f32 v[84:87], v88, v0, v[84:87]
	v_mfma_f32_4x4x1_16b_f32 v[240:243], v89, v1, 0
	s_nop 0
	v_mfma_f32_4x4x1_16b_f32 v[84:87], v90, v2, v[84:87]
	v_mfma_f32_4x4x1_16b_f32 v[240:243], v91, v3, v[240:243]
	s_nop 0
	v_mfma_f32_4x4x1_16b_f32 v[84:87], v92, v4, v[84:87]
	v_mfma_f32_4x4x1_16b_f32 v[240:243], v93, v5, v[240:243]
	s_nop 0
	v_mfma_f32_4x4x1_16b_f32 v[84:87], v94, v6, v[84:87]
	v_mfma_f32_4x4x1_16b_f32 v[240:243], v95, v7, v[240:243]
	s_nop 0
	v_mfma_f32_4x4x1_16b_f32 v[84:87], v96, v8, v[84:87]
	v_mfma_f32_4x4x1_16b_f32 v[240:243], v97, v9, v[240:243]
	s_nop 0
	v_mfma_f32_4x4x1_16b_f32 v[84:87], v98, v10, v[84:87]
	v_mfma_f32_4x4x1_16b_f32 v[240:243], v99, v11, v[240:243]
	s_nop 0
	v_mfma_f32_4x4x1_16b_f32 v[84:87], v100, v12, v[84:87]
	v_mfma_f32_4x4x1_16b_f32 v[240:243], v101, v13, v[240:243]
	s_nop 0
	v_mfma_f32_4x4x1_16b_f32 v[84:87], v102, v14, v[84:87]
	v_mfma_f32_4x4x1_16b_f32 v[240:243], v103, v15, v[240:243]
	s_nop 0
	ds_read_b128 v[88:91], v234 offset:16512
	ds_read_b128 v[92:95], v234 offset:16528
	ds_read_b128 v[96:99], v234 offset:16544
	ds_read_b128 v[100:103], v234 offset:16560
	s_waitcnt lgkmcnt(8)
; #define LAS __attribute__((address_space(3)))
; __device__ __forceinline__ unsigned pk2(float lo, float hi) { const f32x2_t v = {lo, hi}; const bf16x2_t b = __builtin_convertvector(v, bf16x2_t); return __builtin_bit_cast(unsigned, b); }
; __device__ __forceinline__ void dn_prep_item(const Args& a, LAS unsigned char* lds, int item, int tid, int wave, int lane, int& cwh, int next_item) {
;     ...
;         { const LAS float* lrow = Lm + (lane & 15);
; #pragma unroll
;         for (int i = 1; i < 64; ++i) { float sa[4] = { x[i], 0.f, 0.f, 0.f };
;             int lr[4];
; #pragma unroll
;             for (int g = 0; g < (i + 15) / 16; ++g) lr[g] = __float_as_int(lrow[i * 68 + 16 * g]);
; #pragma unroll
;             for (int j = 0; j < i; ++j) { fmac_rowbcast_sel(sa[j & 3], lr[j >> 4], x[j], j); }
;             x[i] = (sa[0] + sa[1]) + (sa[2] + sa[3]); } }
; #pragma unroll
;         for (int q = 0; q < 8; ++q) { v4u w; w.x = pk2(x[8 * q], x[8 * q + 1]); w.y = pk2(x[8 * q + 2], x[8 * q + 3]); w.z = pk2(x[8 * q + 4], x[8 * q + 5]); w.w = pk2(x[8 * q + 6], x[8 * q + 7]);
;             *(LAS v4u*)(lds + L_SOL + tid * AS_ + 16 * q) = w; }
	v_mfma_f32_4x4x1_16b_f32 v[84:87], v104, v16, v[84:87]
	v_mfma_f32_4x4x1_16b_f32 v[240:243], v105, v17, v[240:243]
	s_nop 0
	v_mfma_f32_4x4x1_16b_f32 v[84:87], v106, v18, v[84:87]
	v_mfma_f32_4x4x1_16b_f32 v[240:243], v107, v19, v[240:243]
	s_nop 0
	v_mfma_f32_4x4x1_16b_f32 v[84:87], v108, v20, v[84:87]
	v_mfma_f32_4x4x1_16b_f32 v[240:243], v109, v21, v[240:243]
	s_nop 0
	v_mfma_f32_4x4x1_16b_f32 v[84:87], v110, v22, v[84:87]
	v_mfma_f32_4x4x1_16b_f32 v[240:243], v111, v23, v[240:243]
	s_nop 0
	v_mfma_f32_4x4x1_16b_f32 v[84:87], v112, v24, v[84:87]
	v_mfma_f32_4x4x1_16b_f32 v[240:243], v113, v25, v[240:243]
	s_nop 0
	v_mfma_f32_4x4x1_16b_f32 v[84:87], v114, v26, v[84:87]
	v_mfma_f32_4x4x1_16b_f32 v[240:243], v115, v27, v[240:243]
	s_nop 0
	v_mfma_f32_4x4x1_16b_f32 v[84:87], v116, v28, v[84:87]
	v_mfma_f32_4x4x1_16b_f32 v[240:243], v117, v29, v[240:243]
	s_nop 0
	v_mfma_f32_4x4x1_16b_f32 v[84:87], v118, v30, v[84:87]
	v_mfma_f32_4x4x1_16b_f32 v[240:243], v119, v31, v[240:243]
	s_nop 0
	s_waitcnt lgkmcnt(4)
	v_mfma_f32_4x4x1_16b_f32 v[84:87], v120, v32, v[84:87]
	v_mfma_f32_4x4x1_16b_f32 v[240:243], v121, v33, v[240:243]
	s_nop 0
	v_mfma_f32_4x4x1_16b_f32 v[84:87], v122, v34, v[84:87]
	v_mfma_f32_4x4x1_16b_f32 v[240:243], v123, v35, v[240:243]
	s_nop 0
	v_mfma_f32_4x4x1_16b_f32 v[84:87], v124, v36, v[84:87]
	v_mfma_f32_4x4x1_16b_f32 v[240:243], v125, v37, v[240:243]
	s_nop 0
	v_mfma_f32_4x4x1_16b_f32 v[84:87], v126, v38, v[84:87]
	v_mfma_f32_4x4x1_16b_f32 v[240:243], v127, v39, v[240:243]
	s_nop 0
	v_mfma_f32_4x4x1_16b_f32 v[84:87], v128, v40, v[84:87]
	v_mfma_f32_4x4x1_16b_f32 v[240:243], v129, v41, v[240:243]
	s_nop 0
	v_mfma_f32_4x4x1_16b_f32 v[84:87], v130, v42, v[84:87]
	v_mfma_f32_4x4x1_16b_f32 v[240:243], v131, v43, v[240:243]
	s_nop 0
	v_mfma_f32_4x4x1_16b_f32 v[84:87], v132, v44, v[84:87]
	v_mfma_f32_4x4x1_16b_f32 v[240:243], v133, v45, v[240:243]
	s_nop 0
	v_mfma_f32_4x4x1_16b_f32 v[84:87], v134, v46, v[84:87]
	v_mfma_f32_4x4x1_16b_f32 v[240:243], v135, v47, v[240:243]
	s_nop 0
	s_waitcnt lgkmcnt(0)
	v_mfma_f32_4x4x1_16b_f32 v[84:87], v88, v72, v[84:87]
	v_mfma_f32_4x4x1_16b_f32 v[240:243], v89, v73, v[240:243]
	s_nop 0
	v_mfma_f32_4x4x1_16b_f32 v[84:87], v90, v74, v[84:87]
	v_mfma_f32_4x4x1_16b_f32 v[240:243], v91, v75, v[240:243]
	s_nop 0
	v_mfma_f32_4x4x1_16b_f32 v[84:87], v92, v76, v[84:87]
	v_mfma_f32_4x4x1_16b_f32 v[240:243], v93, v77, v[240:243]
	s_nop 0
	v_mfma_f32_4x4x1_16b_f32 v[84:87], v94, v78, v[84:87]
	v_mfma_f32_4x4x1_16b_f32 v[240:243], v95, v79, v[240:243]
	s_nop 0
	v_mfma_f32_4x4x1_16b_f32 v[84:87], v96, v80, v[84:87]
	v_mfma_f32_4x4x1_16b_f32 v[240:243], v97, v81, v[240:243]
	s_nop 0
	v_mfma_f32_4x4x1_16b_f32 v[84:87], v98, v82, v[84:87]
	v_mfma_f32_4x4x1_16b_f32 v[240:243], v99, v83, v[240:243]
	s_nop 0
	s_nop 3
	v_pk_add_f32 v[84:85], v[84:85], v[240:241]
	v_pk_add_f32 v[86:87], v[86:87], v[242:243]
	s_nop 3
	v_mfma_f32_4x4x1_16b_f32 v[84:87], v100, v84, v[84:87]
	s_nop 3
	v_mfma_f32_4x4x1_16b_f32 v[84:87], v101, v85, v[84:87]
	s_nop 3
	v_mfma_f32_4x4x1_16b_f32 v[84:87], v102, v86, v[84:87]
	s_nop 4
	v_cvt_pk_bf16_f32 v236, v0, v1
	v_cvt_pk_bf16_f32 v237, v2, v3
	v_cvt_pk_bf16_f32 v238, v4, v5
	v_cvt_pk_bf16_f32 v239, v6, v7
	ds_write_b128 v223, v[236:239] offset:61440
	v_cvt_pk_bf16_f32 v236, v8, v9
	v_cvt_pk_bf16_f32 v237, v10, v11
	v_cvt_pk_bf16_f32 v238, v12, v13
	v_cvt_pk_bf16_f32 v239, v14, v15
	ds_write_b128 v223, v[236:239] offset:61456
	v_cvt_pk_bf16_f32 v236, v16, v17
	v_cvt_pk_bf16_f32 v237, v18, v19
	v_cvt_pk_bf16_f32 v238, v20, v21
	v_cvt_pk_bf16_f32 v239, v22, v23
	ds_write_b128 v223, v[236:239] offset:61472
	v_cvt_pk_bf16_f32 v236, v24, v25
	v_cvt_pk_bf16_f32 v237, v26, v27
	v_cvt_pk_bf16_f32 v238, v28, v29
	v_cvt_pk_bf16_f32 v239, v30, v31
	ds_write_b128 v223, v[236:239] offset:61488
	v_cvt_pk_bf16_f32 v236, v32, v33
	v_cvt_pk_bf16_f32 v237, v34, v35
	v_cvt_pk_bf16_f32 v238, v36, v37
	v_cvt_pk_bf16_f32 v239, v38, v39
	ds_write_b128 v223, v[236:239] offset:61504
	v_cvt_pk_bf16_f32 v236, v40, v41
	v_cvt_pk_bf16_f32 v237, v42, v43
	v_cvt_pk_bf16_f32 v238, v44, v45
	v_cvt_pk_bf16_f32 v239, v46, v47
	ds_write_b128 v223, v[236:239] offset:61520
	v_cvt_pk_bf16_f32 v236, v72, v73
	v_cvt_pk_bf16_f32 v237, v74, v75
	v_cvt_pk_bf16_f32 v238, v76, v77
	v_cvt_pk_bf16_f32 v239, v78, v79
	ds_write_b128 v223, v[236:239] offset:61536
	v_cvt_pk_bf16_f32 v236, v80, v81
	v_cvt_pk_bf16_f32 v237, v82, v83
	v_cvt_pk_bf16_f32 v238, v84, v85
	v_cvt_pk_bf16_f32 v239, v86, v87
	ds_write_b128 v223, v[236:239] offset:61552
